# v9: P2 main k-loop staging loads use SGPR-base addressing (drops per-iteration 64-bit VALU address math)
# baseline (speedup 1.0000x reference)
; __device__ __forceinline__ float lo16(unsigned w) { return __uint_as_float(w << 16); }
; template <int AMODE, int BN, class Epi>
; __device__ __forceinline__ void gemm_tile(const bf16_t* A, const int lda, const bf16_t* Bt, const int K, const int m0, const float* mu, char* lds, const Epi& epi) {
;     ...
;   auto gload = [&](int k0) {
; #pragma unroll
;     for (int i = 0; i < 4; ++i) {
;       const bf16_t* ap = A + (size_t)(m0 + srow + 64 * i) * lda + k0 + scc;
;       ra[i] = *(const bf16x8*)ap;
;       if constexpr (AMODE == 1) { rp[i] = *(const bf16x8*)(ap - dprev[i] * lda); rn[i] = *(const bf16x8*)(ap + dnext[i] * lda); }
;     }
; #pragma unroll
;     for (int i = 0; i < NBR; ++i) rb[i] = *(const bf16x8*)(Bt + (size_t)browi[i] * K + k0 + scc);
;   };
;   auto lstore = [&](int s, int k0) {
;     char* base = lds + s * G_STAGE;
;     if constexpr (AMODE == 1) {
;       const f32x4 m0v = *(const f32x4*)(mu + k0 + scc), m1v = *(const f32x4*)(mu + k0 + scc + 4);
;       const float mm[8] = {m0v[0], m0v[1], m0v[2], m0v[3], m1v[0], m1v[1], m1v[2], m1v[3]};
; #pragma unroll
;       for (int i = 0; i < 4; ++i) {
;         const u32x4 hc = *(const u32x4*)&ra[i], hp = *(const u32x4*)&rp[i], hn = *(const u32x4*)&rn[i];
;         const float fp = dprev[i] ? 0.5f : 0.f, fn = dnext[i] ? 0.5f : 0.f;
;         u32x4 w;
; #pragma unroll
;         for (int q = 0; q < 4; ++q) {
;           const float c0 = lo16(hc[q]), c1 = hi16(hc[q]);
;           const float x0 = fp * lo16(hp[q]) + fn * lo16(hn[q]) - c0, x1 = fp * hi16(hp[q]) + fn * hi16(hn[q]) - c1;
;           w[q] = cvtpk(c0 + x0 * mm[2 * q], c1 + x1 * mm[2 * q + 1]);
;         }
;         *(u32x4*)(base + (srow + 64 * i) * G_LDT + scc * 2) = w;
;       }
;     } else {
; #pragma unroll
;       for (int i = 0; i < 4; ++i) {
;         *(bf16x8*)(base + (srow + 64 * i) * G_LDT + scc * 2) = ra[i];
;         if constexpr (AMODE == 2) {
;           const u32x4 hc = *(const u32x4*)&ra[i];
; #pragma unroll
;           for (int q = 0; q < 4; ++q) { const float c0 = lo16(hc[q]), c1 = hi16(hc[q]); ssq[i] += c0 * c0 + c1 * c1; }
;         }
;       }
;     }
; #pragma unroll
;     for (int i = 0; i < NBR; ++i) *(bf16x8*)(base + 256 * G_LDT + (srow + 64 * i) * G_LDT + scc * 2) = rb[i];
;   };
;   const int nk = K >> 6;
;   gload(0);
;   lstore(0, 0);
;   if (nk > 1) gload(64);
;   __syncthreads();
.LBB0_407:
	v_or_b32_e32 v0, s20, v161
	v_ashrrev_i32_e32 v1, 31, v0
	v_lshlrev_b64 v[48:49], 11, v[0:1]
	v_lshl_add_u64 v[2:3], s[16:17], 0, v[48:49]
	v_lshl_add_u64 v[52:53], v[48:49], 0, s[14:15]
	s_lshl_b32 s18, s48, 8
	v_lshl_add_u64 v[50:51], v[2:3], 0, v[170:171]
	v_lshl_add_u64 v[2:3], s[16:17], 0, v[52:53]
	s_and_b32 s21, s18, 0x300
	s_lshl_b32 s18, s4, 10
	v_lshl_add_u64 v[54:55], v[2:3], 0, v[170:171]
	v_or_b32_e32 v2, 0x80, v0
	v_add_u32_e32 v0, 0xc0, v0
	s_or_b32 s18, s21, s18
	v_ashrrev_i32_e32 v1, 31, v0
	s_ashr_i32 s19, s18, 31
	v_lshlrev_b64 v[60:61], 11, v[0:1]
	s_lshl_b64 s[18:19], s[18:19], 11
	v_lshl_add_u64 v[0:1], s[16:17], 0, v[60:61]
	v_lshl_add_u64 v[62:63], v[0:1], 0, v[170:171]
	v_lshl_add_u64 v[0:1], v[164:165], 0, s[18:19]
	v_lshl_add_u64 v[64:65], v[0:1], 0, v[170:171]
	v_add_co_u32_e32 v66, vcc, s34, v64
	v_ashrrev_i32_e32 v3, 31, v2
	s_nop 0
	v_addc_co_u32_e32 v67, vcc, 0, v65, vcc
	v_add_co_u32_e32 v68, vcc, s35, v64
	v_lshlrev_b64 v[56:57], 11, v[2:3]
	s_nop 0
	v_addc_co_u32_e32 v69, vcc, 0, v65, vcc
	v_lshl_add_u64 v[2:3], s[16:17], 0, v[56:57]
	v_add_co_u32_e32 v70, vcc, s43, v64
	v_lshl_add_u64 v[58:59], v[2:3], 0, v[170:171]
	s_nop 0
	v_addc_co_u32_e32 v71, vcc, 0, v65, vcc
	global_load_dwordx4 v[16:19], v[50:51], off
	global_load_dwordx4 v[128:131], v[50:51], off offset:128
	global_load_dwordx4 v[20:23], v[54:55], off
	global_load_dwordx4 v[24:27], v[58:59], off
	global_load_dwordx4 v[28:31], v[62:63], off
	global_load_dwordx4 v[32:35], v[64:65], off
	global_load_dwordx4 v[36:39], v[66:67], off
	global_load_dwordx4 v[40:43], v[68:69], off
	global_load_dwordx4 v[44:47], v[70:71], off
	global_load_dwordx4 v[132:135], v[54:55], off offset:128
	global_load_dwordx4 v[136:139], v[58:59], off offset:128
	global_load_dwordx4 v[140:143], v[62:63], off offset:128
	global_load_dwordx4 v[144:147], v[64:65], off offset:128
	global_load_dwordx4 v[148:151], v[66:67], off offset:128
	global_load_dwordx4 v[152:155], v[68:69], off offset:128
	global_load_dwordx4 v[156:159], v[70:71], off offset:128
	s_mov_b64 s[66:67], s[16:17]
	v_mov_b32_e32 v0, 0
	s_mov_b32 s22, 0
	s_mov_b64 s[16:17], 0
	v_mov_b32_e32 v1, v0
	v_mov_b32_e32 v2, v0
	v_mov_b32_e32 v3, v0
	v_mov_b32_e32 v4, v0
	v_mov_b32_e32 v5, v0
	v_mov_b32_e32 v6, v0
	v_mov_b32_e32 v7, v0
	v_mov_b32_e32 v8, v0
	v_mov_b32_e32 v9, v0
	v_mov_b32_e32 v10, v0
	v_mov_b32_e32 v11, v0
	v_mov_b32_e32 v12, v0
	v_mov_b32_e32 v13, v0
	v_mov_b32_e32 v14, v0
	v_mov_b32_e32 v15, v0
	v_add_u32_e32 v194, v168, v48
	v_add_u32_e32 v196, v168, v60
	v_add_u32_e32 v198, v168, v56
	v_add_u32_e32 v200, v168, v52
	v_subrev_u32_e32 v202, s86, v166
	s_add_u32 s68, s86, s18
	s_addc_u32 s69, s87, s19
	s_add_u32 s68, s68, 0x3c540000
	s_addc_u32 s69, s69, 0
	v_mov_b32_e32 v48, v0
	v_mov_b32_e32 v49, v0
	v_mov_b32_e32 v50, v0
	v_mov_b32_e32 v51, v0
	v_mov_b32_e32 v52, v0
	v_mov_b32_e32 v53, v0
	v_mov_b32_e32 v54, v0
	v_mov_b32_e32 v55, v0
	v_mov_b32_e32 v56, v0
	v_mov_b32_e32 v57, v0
	v_mov_b32_e32 v58, v0
	v_mov_b32_e32 v59, v0
	v_mov_b32_e32 v60, v0
	v_mov_b32_e32 v61, v0
	v_mov_b32_e32 v62, v0
	v_mov_b32_e32 v63, v0
	v_mov_b32_e32 v64, v0
	v_mov_b32_e32 v65, v0
	s_waitcnt vmcnt(15)
	ds_write_b128 v185, v[16:19]
	s_waitcnt vmcnt(13)
	ds_write_b128 v185, v[20:23] offset:9216
	s_waitcnt vmcnt(12)
	ds_write_b128 v185, v[24:27] offset:18432
	s_waitcnt vmcnt(11)
	ds_write_b128 v185, v[28:31] offset:27648
	s_waitcnt vmcnt(10)
	ds_write_b128 v185, v[32:35] offset:36864
	s_waitcnt vmcnt(9)
	ds_write_b128 v185, v[36:39] offset:46080
	s_waitcnt vmcnt(8)
	ds_write_b128 v185, v[40:43] offset:55296
	s_waitcnt vmcnt(7)
	ds_write_b128 v185, v[44:47] offset:64512
	v_mov_b32_e32 v16, v0
	v_mov_b32_e32 v17, v0
	v_mov_b32_e32 v18, v0
	v_mov_b32_e32 v19, v0
	v_mov_b32_e32 v20, v0
	v_mov_b32_e32 v21, v0
	v_mov_b32_e32 v22, v0
	v_mov_b32_e32 v23, v0
	v_mov_b32_e32 v24, v0
	v_mov_b32_e32 v25, v0
	v_mov_b32_e32 v26, v0
	v_mov_b32_e32 v27, v0
	v_mov_b32_e32 v28, v0
	v_mov_b32_e32 v29, v0
	v_mov_b32_e32 v30, v0
	v_mov_b32_e32 v31, v0
	v_mov_b32_e32 v32, v0
	v_mov_b32_e32 v33, v0
	v_mov_b32_e32 v34, v0
	v_mov_b32_e32 v35, v0
	v_mov_b32_e32 v36, v0
	v_mov_b32_e32 v37, v0
	v_mov_b32_e32 v38, v0
	v_mov_b32_e32 v39, v0
	v_mov_b32_e32 v40, v0
	v_mov_b32_e32 v41, v0
	v_mov_b32_e32 v42, v0
	v_mov_b32_e32 v43, v0
	v_mov_b32_e32 v44, v0
	v_mov_b32_e32 v45, v0
	v_mov_b32_e32 v46, v0
	v_mov_b32_e32 v47, v0
	v_mov_b32_e32 v66, v0
	v_mov_b32_e32 v67, v0
	v_mov_b32_e32 v68, v0
	v_mov_b32_e32 v69, v0
	v_mov_b32_e32 v70, v0
	v_mov_b32_e32 v71, v0
	v_mov_b32_e32 v72, v0
	v_mov_b32_e32 v73, v0
	v_mov_b32_e32 v74, v0
	v_mov_b32_e32 v75, v0
	v_mov_b32_e32 v76, v0
	v_mov_b32_e32 v77, v0
	v_mov_b32_e32 v78, v0
	v_mov_b32_e32 v79, v0
	v_mov_b32_e32 v80, v0
	v_mov_b32_e32 v81, v0
	v_mov_b32_e32 v82, v0
	v_mov_b32_e32 v83, v0
	v_mov_b32_e32 v84, v0
	v_mov_b32_e32 v85, v0
	v_mov_b32_e32 v86, v0
	v_mov_b32_e32 v87, v0
	v_mov_b32_e32 v88, v0
	v_mov_b32_e32 v89, v0
	v_mov_b32_e32 v90, v0
	v_mov_b32_e32 v91, v0
	v_mov_b32_e32 v92, v0
	v_mov_b32_e32 v93, v0
	v_mov_b32_e32 v94, v0
	v_mov_b32_e32 v95, v0
	v_mov_b32_e32 v96, v0
	v_mov_b32_e32 v97, v0
	v_mov_b32_e32 v98, v0
	v_mov_b32_e32 v99, v0
	v_mov_b32_e32 v100, v0
	v_mov_b32_e32 v101, v0
	v_mov_b32_e32 v102, v0
	v_mov_b32_e32 v103, v0
	v_mov_b32_e32 v104, v0
	v_mov_b32_e32 v105, v0
	v_mov_b32_e32 v106, v0
	v_mov_b32_e32 v107, v0
	v_mov_b32_e32 v108, v0
	v_mov_b32_e32 v109, v0
	v_mov_b32_e32 v110, v0
	v_mov_b32_e32 v111, v0
	v_mov_b32_e32 v112, v0
	v_mov_b32_e32 v113, v0
	v_mov_b32_e32 v114, v0
	v_mov_b32_e32 v115, v0
	v_mov_b32_e32 v116, v0
	v_mov_b32_e32 v117, v0
	v_mov_b32_e32 v118, v0
	v_mov_b32_e32 v119, v0
	v_mov_b32_e32 v120, v0
	v_mov_b32_e32 v121, v0
	v_mov_b32_e32 v122, v0
	v_mov_b32_e32 v123, v0
	v_mov_b32_e32 v124, v0
	v_mov_b32_e32 v125, v0
	v_mov_b32_e32 v126, v0
	v_mov_b32_e32 v127, v0
	s_waitcnt lgkmcnt(0)
	s_barrier
	v_readfirstlane_b32 s61, v178
	s_nop 0
	s_cmpk_lt_u32 s61, 0x100
	s_cbranch_scc0 .LppP2_B

; template <int AMODE, int BN, class Epi>
; __device__ __forceinline__ void gemm_tile(const bf16_t* A, const int lda, const bf16_t* Bt, const int K, const int m0, const float* mu, char* lds, const Epi& epi) {
;     ...
;   auto gload = [&](int k0) {
; #pragma unroll
;     for (int i = 0; i < 4; ++i) {
;       const bf16_t* ap = A + (size_t)(m0 + srow + 64 * i) * lda + k0 + scc;
;       ra[i] = *(const bf16x8*)ap;
;       if constexpr (AMODE == 1) { rp[i] = *(const bf16x8*)(ap - dprev[i] * lda); rn[i] = *(const bf16x8*)(ap + dnext[i] * lda); }
;     }
; #pragma unroll
;     for (int i = 0; i < NBR; ++i) rb[i] = *(const bf16x8*)(Bt + (size_t)browi[i] * K + k0 + scc);
;   };
.LppP2_nowA:
	s_cmp_gt_u32 s22, 13
	s_cbranch_scc1 .LppP2_nogA
	s_add_u32 s72, s66, s16
	s_addc_u32 s73, s67, s17
	s_add_u32 s78, s68, s16
	s_addc_u32 s79, s69, s17
	s_add_u32 s90, s78, 0x20000
	s_addc_u32 s91, s79, 0
	s_add_u32 s94, s78, 0x40000
	s_addc_u32 s95, s79, 0
	s_add_u32 s96, s78, 0x60000
	s_addc_u32 s97, s79, 0
	global_load_dwordx4 v[128:131], v194, s[72:73]
	global_load_dwordx4 v[132:135], v200, s[72:73]
	global_load_dwordx4 v[136:139], v198, s[72:73]
	global_load_dwordx4 v[140:143], v196, s[72:73]
	global_load_dwordx4 v[144:147], v202, s[78:79] offset:256
	global_load_dwordx4 v[148:151], v202, s[90:91] offset:256
	global_load_dwordx4 v[152:155], v202, s[94:95] offset:256
	global_load_dwordx4 v[156:159], v202, s[96:97] offset:256


